# grid barrier: non-leader workgroups poll the top-level generation word directly (one signalling hop fewer)
# speedup vs baseline: 1.0100x; 1.0100x over previous
.LBB0_387:
	s_or_b64 exec, exec, s[10:11]
	v_cvt_f32_u32_e32 v5, v3
	s_waitcnt vmcnt(0)
	v_readfirstlane_b32 s8, v4
	v_sub_u32_e32 v4, 0, v3
	v_rcp_iflag_f32_e32 v5, v5
	v_add_u32_e32 v6, s8, v0
	v_mul_f32_e32 v5, 0x4f7ffffe, v5
	v_cvt_u32_f32_e32 v5, v5
	v_mul_lo_u32 v0, v4, v5
	v_mul_hi_u32 v0, v5, v0
	v_add_u32_e32 v0, v5, v0
	v_mul_hi_u32 v0, v6, v0
	v_mul_lo_u32 v4, v0, v3
	v_sub_u32_e32 v4, v6, v4
	v_add_u32_e32 v5, 1, v0
	v_cmp_ge_u32_e32 vcc, v4, v3
	s_nop 1
	v_cndmask_b32_e32 v0, v0, v5, vcc
	v_sub_u32_e32 v5, v4, v3
	v_cndmask_b32_e32 v4, v4, v5, vcc
	v_add_u32_e32 v5, 1, v0
	v_cmp_ge_u32_e32 vcc, v4, v3
	v_add_u32_e32 v4, 1, v6
	s_nop 0
	v_cndmask_b32_e32 v0, v0, v5, vcc
	v_mul_lo_u32 v5, v3, v0
	v_add_u32_e32 v3, v5, v3
	v_cmp_ne_u32_e32 vcc, v4, v3
	s_and_saveexec_b64 s[8:9], vcc
	s_xor_b64 s[8:9], exec, s[8:9]
	s_cbranch_execz .LBB0_401
	s_waitcnt lgkmcnt(0)
	s_add_u32 s14, s4, 0x4500
	s_addc_u32 s15, s5, 0
	global_load_dword v2, v1, s[14:15] sc1
	s_waitcnt vmcnt(0)
	v_cmp_eq_u32_e32 vcc, v2, v0
	s_and_saveexec_b64 s[10:11], vcc
	s_cbranch_execz .LBB0_400
	s_add_u32 s12, s4, 0x1200
	s_addc_u32 s13, s5, 0
	s_mov_b32 s26, 1
	s_mov_b64 s[16:17], 0
	s_branch .LBB0_391
